# gu ctx ring: next tile's first two k-stages DMA issued before the current tile's SwiGLU epilogue (cross-tile prefetch), counted vmcnt past the epilogue stores
# speedup vs baseline: 1.0084x; 1.0005x over previous
; #define TIDX opaque_tid()
; template <int AI, int BI>
; DI void gemm_stage(const u16* __restrict__ A, int lda, const u16* __restrict__ B, int ldb, char* buf, int tid) {
; #pragma unroll
;   for (int i = 0; i < 2 * AI; ++i) {
;     const int S = tid + NTHR * i, row = S >> 3, c = (S & 7) ^ ((row >> 1) & 7);
;     __builtin_amdgcn_global_load_lds((const unsigned*)(A + (size_t)row * lda + c * 8), (__attribute__((address_space(3))) unsigned*)(buf + S * 16), 16, 0, 0);
;   }
; #pragma unroll
;   for (int i = 0; i < 2 * BI; ++i) {
;     const int S = tid + NTHR * i, row = S >> 3, c = (S & 7) ^ ((row >> 1) & 7);
;     __builtin_amdgcn_global_load_lds((const unsigned*)(B + (size_t)row * ldb + c * 8), (__attribute__((address_space(3))) unsigned*)(buf + 16384 + S * 16), 16, 0, 0);
;   }
; }
; template <int AI, int BI>
; DI void gemm_tile(const u16* __restrict__ A, int lda, const u16* __restrict__ B, int ldb, int nk, bool swap,
;                   f32x16 (&acc)[AI][BI], char* lds) {
;   const int tid = TIDX, lane = tid & 63, wid = tid >> 6;
;   gemm_stage<AI, BI>(A, lda, B, ldb, lds, tid);
;   asm volatile("s_waitcnt vmcnt(0)" ::: "memory");
;   __syncthreads();
;   const int wa = wid >> 1, wb = wid & 1, r = lane & 31, h = lane >> 5, sw = (r >> 1) & 7;
;   const int offA = (swap ? 16384 : 0) + (wa * 32 * AI + r) * 128;
;   const int offB = (swap ? 0 : 16384) + (wb * 32 * BI + r) * 128;
; template <int AI, int BI>
; DI void zero_acc(f32x16 (&acc)[AI][BI]) {
; #pragma unroll
;   for (int a = 0; a < AI; ++a)
; #pragma unroll
;     for (int b = 0; b < BI; ++b)
; #pragma unroll
;       for (int i = 0; i < 16; ++i) acc[a][b][i] = 0.f;
; }
.LBB0_421:
	v_readlane_b32 s6, v244, 50
	v_readlane_b32 s7, v244, 51
	s_andn2_b64 vcc, exec, s[6:7]
	s_mov_b32 s49, 0x1ffffe0
	s_cbranch_vccnz .LBB0_425
	s_add_u32 s10, s8, 0x77b7000
	s_addc_u32 s11, s9, 0
	s_add_u32 s12, s8, 0x1c4b7000
	s_addc_u32 s13, s9, 0
	s_add_u32 s6, s8, 0x9bb7000
	s_addc_u32 s7, s9, 0
	v_readlane_b32 s14, v243, 18
	v_readlane_b32 s15, v243, 10
	v_readlane_b32 s16, v243, 8
	v_readlane_b32 s48, v243, 7
	s_mov_b64 s[50:51], 0x200
	s_mov_b64 s[52:53], 0x80
	s_mov_b64 s[54:55], 0x180
	s_mov_b64 s[64:65], 0x300
	s_mov_b64 s[66:67], 0x380
	s_mov_b64 s[68:69], 0x400
	s_mov_b64 s[70:71], 0x480
	s_mov_b64 s[72:73], 0x500
	s_mov_b64 s[74:75], 0x580
	s_mov_b64 s[76:77], 0x600
	s_mov_b64 s[56:57], 0x280
	s_cmpk_lg_u32 s92, 0x200
	s_cbranch_scc1 .LBB0_423
	v_and_b32_e32 v95, 31, v178
	v_bfe_u32 v96, v178, 5, 1
	v_bfe_u32 v97, v178, 1, 3
	v_bfe_u32 v98, v178, 7, 1
	v_lshl_add_u32 v98, v98, 5, v95
	v_lshlrev_b32_e32 v98, 7, v98
	v_add_u32_e32 v98, 0xc000, v98
	v_bfe_u32 v99, v178, 6, 1
	v_lshl_add_u32 v99, v99, 6, v95
	v_lshlrev_b32_e32 v99, 7, v99
	v_mov_b32_e32 v0, v96
	v_xor_b32_e32 v0, v0, v97
	v_lshlrev_b32_e32 v0, 4, v0
	v_add_u32_e32 v82, v98, v0
	v_add_u32_e32 v86, v99, v0
	v_add_u32_e32 v0, 2, v96
	v_xor_b32_e32 v0, v0, v97
	v_lshlrev_b32_e32 v0, 4, v0
	v_add_u32_e32 v83, v98, v0
	v_add_u32_e32 v87, v99, v0
	v_add_u32_e32 v0, 4, v96
	v_xor_b32_e32 v0, v0, v97
	v_lshlrev_b32_e32 v0, 4, v0
	v_add_u32_e32 v84, v98, v0
	v_add_u32_e32 v88, v99, v0
	v_add_u32_e32 v0, 6, v96
	v_xor_b32_e32 v0, v0, v97
	v_lshlrev_b32_e32 v0, 4, v0
	v_add_u32_e32 v85, v98, v0
	v_add_u32_e32 v89, v99, v0
	v_bfe_u32 v96, v178, 7, 1
	v_lshlrev_b32_e32 v96, 5, v96
	v_bfe_u32 v97, v178, 5, 1
	v_lshl_add_u32 v96, v97, 2, v96
	v_mul_u32_u24_e32 v96, 0xb00, v96
	v_bfe_u32 v97, v178, 6, 1
	v_lshl_add_u32 v97, v97, 5, v95
	v_add_u32_e32 v96, v96, v97
	v_lshlrev_b32_e32 v94, 1, v96
	v_lshrrev_b32_e32 v95, 3, v178
	v_and_b32_e32 v96, 7, v178
	v_bfe_u32 v97, v178, 4, 3
	v_xor_b32_e32 v96, v96, v97
	v_lshlrev_b32_e32 v96, 4, v96
	v_lshl_add_u32 v90, v95, 11, v96
	v_add_u32_e32 v91, 0x10000, v90
	v_add_u32_e32 v92, 0x20000, v90
	v_add_u32_e32 v93, 0x30000, v90
	v_lshrrev_b32_e32 v95, 6, v178
	s_nop 1
	v_readfirstlane_b32 s17, v95
	s_lshl_b32 s17, s17, 10
	s_mov_b32 s36, s14
	s_mul_i32 s37, s36, 0xba2f
	s_lshr_b32 s37, s37, 24
	s_mul_i32 s40, s37, 0x160
	s_sub_u32 s40, s36, s40
	s_lshr_b32 s41, s40, 3
	s_and_b32 s40, s40, 7
	s_lshl_b32 s37, s37, 3
	s_or_b32 s37, s37, s40
	s_lshl_b32 s37, s37, 6
	s_bitset1_b32 s37, 14
	s_lshl_b32 s46, s37, 11
	s_add_u32 s8, s10, s46
	s_addc_u32 s9, s11, 0
	s_lshl_b32 s46, s41, 18
	s_add_u32 s28, s12, s46
	s_addc_u32 s29, s13, 0
	s_barrier
	s_add_u32 m0, s17, 49152
	s_nop 0
	global_load_lds_dwordx4 v90, s[8:9]
	s_add_u32 m0, s17, 53248
	s_nop 0
	global_load_lds_dwordx4 v91, s[8:9]
	s_add_u32 m0, s17, 0
	s_nop 0
	global_load_lds_dwordx4 v90, s[28:29]
	s_add_u32 m0, s17, 4096
	s_nop 0
	global_load_lds_dwordx4 v91, s[28:29]
	s_add_u32 m0, s17, 8192
	s_nop 0
	global_load_lds_dwordx4 v92, s[28:29]
	s_add_u32 m0, s17, 12288
	s_nop 0
	global_load_lds_dwordx4 v93, s[28:29]
	s_add_u32 s8, s8, 0x80
	s_addc_u32 s9, s9, 0
	s_add_u32 s28, s28, 0x80
	s_addc_u32 s29, s29, 0
	s_add_u32 m0, s17, 57344
	s_nop 0
	global_load_lds_dwordx4 v90, s[8:9]
	s_add_u32 m0, s17, 61440
	s_nop 0
	global_load_lds_dwordx4 v91, s[8:9]
	s_add_u32 m0, s17, 16384
	s_nop 0
	global_load_lds_dwordx4 v90, s[28:29]
	s_add_u32 m0, s17, 20480
	s_nop 0
	global_load_lds_dwordx4 v91, s[28:29]
	s_add_u32 m0, s17, 24576
	s_nop 0
	global_load_lds_dwordx4 v92, s[28:29]
	s_add_u32 m0, s17, 28672
	s_nop 0
	global_load_lds_dwordx4 v93, s[28:29]
	s_add_u32 s8, s8, 0x80
	s_addc_u32 s9, s9, 0
	s_add_u32 s28, s28, 0x80
	s_addc_u32 s29, s29, 0
	s_mov_b32 s32, 0
.Lgc1_tile:
	s_mul_i32 s37, s36, 0xba2f
	s_lshr_b32 s37, s37, 24
	s_mul_i32 s40, s37, 0x160
	s_sub_u32 s40, s36, s40
	s_lshr_b32 s41, s40, 3
	s_and_b32 s40, s40, 7
	s_lshl_b32 s37, s37, 3
	s_or_b32 s37, s37, s40
	s_lshl_b32 s37, s37, 6
	s_bitset1_b32 s37, 14
	s_mul_i32 s46, s37, 0x1600
	s_lshl_b32 s47, s41, 7
	s_add_u32 s46, s46, s47
	s_add_u32 s34, s6, s46
	s_addc_u32 s35, s7, 0
	v_mov_b32_e32 v2, 0
	v_mov_b32_e32 v3, 0
	v_mov_b32_e32 v4, 0
	v_mov_b32_e32 v5, 0
	v_mov_b32_e32 v6, 0
	v_mov_b32_e32 v7, 0
	v_mov_b32_e32 v8, 0
	v_mov_b32_e32 v9, 0
	v_mov_b32_e32 v10, 0
	v_mov_b32_e32 v11, 0
	v_mov_b32_e32 v12, 0
	v_mov_b32_e32 v13, 0
	v_mov_b32_e32 v14, 0
	v_mov_b32_e32 v15, 0
	v_mov_b32_e32 v16, 0
	v_mov_b32_e32 v17, 0
	v_mov_b32_e32 v18, 0
	v_mov_b32_e32 v19, 0
	v_mov_b32_e32 v20, 0
	v_mov_b32_e32 v21, 0
	v_mov_b32_e32 v22, 0
	v_mov_b32_e32 v23, 0
	v_mov_b32_e32 v24, 0
	v_mov_b32_e32 v25, 0
	v_mov_b32_e32 v26, 0
	v_mov_b32_e32 v27, 0
	v_mov_b32_e32 v28, 0
	v_mov_b32_e32 v29, 0
	v_mov_b32_e32 v30, 0
	v_mov_b32_e32 v31, 0
	v_mov_b32_e32 v32, 0
	v_mov_b32_e32 v33, 0
	s_cmp_eq_u32 s32, 0
	s_cbranch_scc1 .Lgc1_w0_f
	s_waitcnt vmcnt(22)
	s_branch .Lgc1_w0_j

; #define MFMA(a, b, c) __builtin_amdgcn_mfma_f32_32x32x16_bf16((a), (b), (c), 0, 0, 0)
; template <int AI, int BI>
; DI void gemm_tile(const u16* __restrict__ A, int lda, const u16* __restrict__ B, int ldb, int nk, bool swap,
;                   f32x16 (&acc)[AI][BI], char* lds) {
;     ...
;   for (int kt = 0; kt < nk; ++kt) {
;     const char* cur = lds + (kt & 1) * 32768;
;     if (kt + 1 < nk) gemm_stage<AI, BI>(A + (kt + 1) * 64, lda, B + (kt + 1) * 64, ldb, lds + ((kt + 1) & 1) * 32768, tid);
; #pragma unroll
;     for (int ks = 0; ks < 4; ++ks) {
;       const int co = ((ks * 2 + h) ^ sw) << 4;
;       s16x8 fa[AI], fb[BI];
; #pragma unroll
;       for (int i = 0; i < AI; ++i) fa[i] = *(const s16x8*)(cur + offA + i * 4096 + co);
; #pragma unroll
;       for (int i = 0; i < BI; ++i) fb[i] = *(const s16x8*)(cur + offB + i * 4096 + co);
; #pragma unroll
;       for (int i = 0; i < AI; ++i)
; #pragma unroll
;         for (int j = 0; j < BI; ++j) acc[i][j] = MFMA(fa[i], fb[j], acc[i][j]);
;     }
;     asm volatile("s_waitcnt vmcnt(0)" ::: "memory");
;     __syncthreads();
;   }
.Lgc1_w0_j:
	s_barrier
	s_add_u32 m0, s17, 65664
	s_nop 0
	global_load_lds_dwordx4 v90, s[8:9]
	s_add_u32 m0, s17, 69760
	s_nop 0
	global_load_lds_dwordx4 v91, s[8:9]
	s_add_u32 m0, s17, 32768
	s_nop 0
	global_load_lds_dwordx4 v90, s[28:29]
	s_add_u32 m0, s17, 36864
	s_nop 0
	global_load_lds_dwordx4 v91, s[28:29]
	s_add_u32 m0, s17, 40960
	s_nop 0
	global_load_lds_dwordx4 v92, s[28:29]
	s_add_u32 m0, s17, 45056
	s_nop 0
	global_load_lds_dwordx4 v93, s[28:29]
	s_add_u32 s8, s8, 0x80
	s_addc_u32 s9, s9, 0
	s_add_u32 s28, s28, 0x80
	s_addc_u32 s29, s29, 0
	ds_read_b128 v[34:37], v82 offset:0
	ds_read_b128 v[38:41], v86 offset:0
	ds_read_b128 v[42:45], v86 offset:4096
	ds_read_b128 v[46:49], v83 offset:0
	ds_read_b128 v[50:53], v87 offset:0
	ds_read_b128 v[54:57], v87 offset:4096
	ds_read_b128 v[58:61], v84 offset:0
	ds_read_b128 v[62:65], v88 offset:0
	ds_read_b128 v[66:69], v88 offset:4096
	ds_read_b128 v[70:73], v85 offset:0
	ds_read_b128 v[74:77], v89 offset:0
	ds_read_b128 v[78:81], v89 offset:4096
	s_waitcnt lgkmcnt(10)
	v_mfma_f32_32x32x16_bf16 v[2:17], v[34:37], v[38:41], v[2:17]
	s_waitcnt lgkmcnt(9)
	v_mfma_f32_32x32x16_bf16 v[18:33], v[34:37], v[42:45], v[18:33]
	s_waitcnt lgkmcnt(7)
	v_mfma_f32_32x32x16_bf16 v[2:17], v[46:49], v[50:53], v[2:17]
	s_waitcnt lgkmcnt(6)
	v_mfma_f32_32x32x16_bf16 v[18:33], v[46:49], v[54:57], v[18:33]
	s_waitcnt lgkmcnt(4)
	v_mfma_f32_32x32x16_bf16 v[2:17], v[58:61], v[62:65], v[2:17]
	s_waitcnt lgkmcnt(3)
	v_mfma_f32_32x32x16_bf16 v[18:33], v[58:61], v[66:69], v[18:33]
	s_waitcnt lgkmcnt(1)
	v_mfma_f32_32x32x16_bf16 v[2:17], v[70:73], v[74:77], v[2:17]
	s_waitcnt lgkmcnt(0)
	v_mfma_f32_32x32x16_bf16 v[18:33], v[70:73], v[78:81], v[18:33]
	s_cmp_eq_u32 s32, 0
	s_cbranch_scc1 .Lgc1_w1_f
	s_waitcnt vmcnt(22)
	s_branch .Lgc1_w1_j

; #define MFMA(a, b, c) __builtin_amdgcn_mfma_f32_32x32x16_bf16((a), (b), (c), 0, 0, 0)
; template <int AI, int BI>
; DI void gemm_stage(const u16* __restrict__ A, int lda, const u16* __restrict__ B, int ldb, char* buf, int tid) {
; #pragma unroll
;   for (int i = 0; i < 2 * AI; ++i) {
;     const int S = tid + NTHR * i, row = S >> 3, c = (S & 7) ^ ((row >> 1) & 7);
;     __builtin_amdgcn_global_load_lds((const unsigned*)(A + (size_t)row * lda + c * 8), (__attribute__((address_space(3))) unsigned*)(buf + S * 16), 16, 0, 0);
;   }
; #pragma unroll
;   for (int i = 0; i < 2 * BI; ++i) {
;     const int S = tid + NTHR * i, row = S >> 3, c = (S & 7) ^ ((row >> 1) & 7);
;     __builtin_amdgcn_global_load_lds((const unsigned*)(B + (size_t)row * ldb + c * 8), (__attribute__((address_space(3))) unsigned*)(buf + 16384 + S * 16), 16, 0, 0);
;   }
; }
; template <int AI, int BI>
; DI void gemm_tile(const u16* __restrict__ A, int lda, const u16* __restrict__ B, int ldb, int nk, bool swap,
;                   f32x16 (&acc)[AI][BI], char* lds) {
;     ...
;   for (int kt = 0; kt < nk; ++kt) {
;     const char* cur = lds + (kt & 1) * 32768;
;     if (kt + 1 < nk) gemm_stage<AI, BI>(A + (kt + 1) * 64, lda, B + (kt + 1) * 64, ldb, lds + ((kt + 1) & 1) * 32768, tid);
; #pragma unroll
;     for (int ks = 0; ks < 4; ++ks) {
;       const int co = ((ks * 2 + h) ^ sw) << 4;
;       s16x8 fa[AI], fb[BI];
; #pragma unroll
;       for (int i = 0; i < AI; ++i) fa[i] = *(const s16x8*)(cur + offA + i * 4096 + co);
; #pragma unroll
;       for (int i = 0; i < BI; ++i) fb[i] = *(const s16x8*)(cur + offB + i * 4096 + co);
; #pragma unroll
;       for (int i = 0; i < AI; ++i)
; #pragma unroll
;         for (int j = 0; j < BI; ++j) acc[i][j] = MFMA(fa[i], fb[j], acc[i][j]);
;     }
;     asm volatile("s_waitcnt vmcnt(0)" ::: "memory");
;     __syncthreads();
.Lgc1_w1_j:
	s_barrier
	s_add_u32 m0, s17, 49152
	s_nop 0
	global_load_lds_dwordx4 v90, s[8:9]
	s_add_u32 m0, s17, 53248
	s_nop 0
	global_load_lds_dwordx4 v91, s[8:9]
	s_add_u32 m0, s17, 0
	s_nop 0
	global_load_lds_dwordx4 v90, s[28:29]
	s_add_u32 m0, s17, 4096
	s_nop 0
	global_load_lds_dwordx4 v91, s[28:29]
	s_add_u32 m0, s17, 8192
	s_nop 0
	global_load_lds_dwordx4 v92, s[28:29]
	s_add_u32 m0, s17, 12288
	s_nop 0
	global_load_lds_dwordx4 v93, s[28:29]
	s_add_u32 s8, s8, 0x80
	s_addc_u32 s9, s9, 0
	s_add_u32 s28, s28, 0x80
	s_addc_u32 s29, s29, 0
	ds_read_b128 v[34:37], v82 offset:8192
	ds_read_b128 v[38:41], v86 offset:16384
	ds_read_b128 v[42:45], v86 offset:20480
	ds_read_b128 v[46:49], v83 offset:8192
	ds_read_b128 v[50:53], v87 offset:16384
	ds_read_b128 v[54:57], v87 offset:20480
	ds_read_b128 v[58:61], v84 offset:8192
	ds_read_b128 v[62:65], v88 offset:16384
	ds_read_b128 v[66:69], v88 offset:20480
	ds_read_b128 v[70:73], v85 offset:8192
	ds_read_b128 v[74:77], v89 offset:16384
	ds_read_b128 v[78:81], v89 offset:20480
	s_waitcnt lgkmcnt(10)
	v_mfma_f32_32x32x16_bf16 v[2:17], v[34:37], v[38:41], v[2:17]
	s_waitcnt lgkmcnt(9)
	v_mfma_f32_32x32x16_bf16 v[18:33], v[34:37], v[42:45], v[18:33]
	s_waitcnt lgkmcnt(7)
	v_mfma_f32_32x32x16_bf16 v[2:17], v[46:49], v[50:53], v[2:17]
	s_waitcnt lgkmcnt(6)
	v_mfma_f32_32x32x16_bf16 v[18:33], v[46:49], v[54:57], v[18:33]
	s_waitcnt lgkmcnt(4)
	v_mfma_f32_32x32x16_bf16 v[2:17], v[58:61], v[62:65], v[2:17]
	s_waitcnt lgkmcnt(3)
	v_mfma_f32_32x32x16_bf16 v[18:33], v[58:61], v[66:69], v[18:33]
	s_waitcnt lgkmcnt(1)
	v_mfma_f32_32x32x16_bf16 v[2:17], v[70:73], v[74:77], v[2:17]
	s_waitcnt lgkmcnt(0)
	v_mfma_f32_32x32x16_bf16 v[18:33], v[70:73], v[78:81], v[18:33]
	s_waitcnt vmcnt(6)
	s_barrier
	s_add_u32 m0, s17, 57344
	s_nop 0
	global_load_lds_dwordx4 v90, s[8:9]
	s_add_u32 m0, s17, 61440
	s_nop 0
	global_load_lds_dwordx4 v91, s[8:9]
	s_add_u32 m0, s17, 16384
	s_nop 0
	global_load_lds_dwordx4 v90, s[28:29]
	s_add_u32 m0, s17, 20480
	s_nop 0
	global_load_lds_dwordx4 v91, s[28:29]
	s_add_u32 m0, s17, 24576
	s_nop 0
	global_load_lds_dwordx4 v92, s[28:29]
	s_add_u32 m0, s17, 28672
	s_nop 0
	global_load_lds_dwordx4 v93, s[28:29]
	s_add_u32 s8, s8, 0x80
	s_addc_u32 s9, s9, 0
	s_add_u32 s28, s28, 0x80
	s_addc_u32 s29, s29, 0
	ds_read_b128 v[34:37], v82 offset:16512
	ds_read_b128 v[38:41], v86 offset:32768
	ds_read_b128 v[42:45], v86 offset:36864
	ds_read_b128 v[46:49], v83 offset:16512
	ds_read_b128 v[50:53], v87 offset:32768
	ds_read_b128 v[54:57], v87 offset:36864
	ds_read_b128 v[58:61], v84 offset:16512
	ds_read_b128 v[62:65], v88 offset:32768
	ds_read_b128 v[66:69], v88 offset:36864
	ds_read_b128 v[70:73], v85 offset:16512
	ds_read_b128 v[74:77], v89 offset:32768
	ds_read_b128 v[78:81], v89 offset:36864
	s_waitcnt lgkmcnt(10)
	v_mfma_f32_32x32x16_bf16 v[2:17], v[34:37], v[38:41], v[2:17]
	s_waitcnt lgkmcnt(9)
	v_mfma_f32_32x32x16_bf16 v[18:33], v[34:37], v[42:45], v[18:33]
	s_waitcnt lgkmcnt(7)
	v_mfma_f32_32x32x16_bf16 v[2:17], v[46:49], v[50:53], v[2:17]
	s_waitcnt lgkmcnt(6)
	v_mfma_f32_32x32x16_bf16 v[18:33], v[46:49], v[54:57], v[18:33]
	s_waitcnt lgkmcnt(4)
	v_mfma_f32_32x32x16_bf16 v[2:17], v[58:61], v[62:65], v[2:17]
	s_waitcnt lgkmcnt(3)
	v_mfma_f32_32x32x16_bf16 v[18:33], v[58:61], v[66:69], v[18:33]
	s_waitcnt lgkmcnt(1)
	v_mfma_f32_32x32x16_bf16 v[2:17], v[70:73], v[74:77], v[2:17]
	s_waitcnt lgkmcnt(0)
	v_mfma_f32_32x32x16_bf16 v[18:33], v[70:73], v[78:81], v[18:33]
	s_mov_b32 s18, 3
.Lgc1_kloop:
	s_waitcnt vmcnt(6)
	s_barrier
	s_add_u32 m0, s17, 65664
	s_nop 0
	global_load_lds_dwordx4 v90, s[8:9]
	s_add_u32 m0, s17, 69760
	s_nop 0
	global_load_lds_dwordx4 v91, s[8:9]
	s_add_u32 m0, s17, 32768
	s_nop 0
	global_load_lds_dwordx4 v90, s[28:29]
	s_add_u32 m0, s17, 36864
	s_nop 0
	global_load_lds_dwordx4 v91, s[28:29]
	s_add_u32 m0, s17, 40960
	s_nop 0
	global_load_lds_dwordx4 v92, s[28:29]
	s_add_u32 m0, s17, 45056
	s_nop 0
	global_load_lds_dwordx4 v93, s[28:29]
	s_add_u32 s8, s8, 0x80
	s_addc_u32 s9, s9, 0
	s_add_u32 s28, s28, 0x80
	s_addc_u32 s29, s29, 0
	ds_read_b128 v[34:37], v82 offset:0
	ds_read_b128 v[38:41], v86 offset:0
	ds_read_b128 v[42:45], v86 offset:4096
	ds_read_b128 v[46:49], v83 offset:0
	ds_read_b128 v[50:53], v87 offset:0
	ds_read_b128 v[54:57], v87 offset:4096
	ds_read_b128 v[58:61], v84 offset:0
	ds_read_b128 v[62:65], v88 offset:0
	ds_read_b128 v[66:69], v88 offset:4096
	ds_read_b128 v[70:73], v85 offset:0
	ds_read_b128 v[74:77], v89 offset:0
	ds_read_b128 v[78:81], v89 offset:4096
	s_waitcnt lgkmcnt(10)
	v_mfma_f32_32x32x16_bf16 v[2:17], v[34:37], v[38:41], v[2:17]
	s_waitcnt lgkmcnt(9)
	v_mfma_f32_32x32x16_bf16 v[18:33], v[34:37], v[42:45], v[18:33]
	s_waitcnt lgkmcnt(7)
	v_mfma_f32_32x32x16_bf16 v[2:17], v[46:49], v[50:53], v[2:17]
	s_waitcnt lgkmcnt(6)
	v_mfma_f32_32x32x16_bf16 v[18:33], v[46:49], v[54:57], v[18:33]
	s_waitcnt lgkmcnt(4)
	v_mfma_f32_32x32x16_bf16 v[2:17], v[58:61], v[62:65], v[2:17]
	s_waitcnt lgkmcnt(3)
	v_mfma_f32_32x32x16_bf16 v[18:33], v[58:61], v[66:69], v[18:33]
	s_waitcnt lgkmcnt(1)
	v_mfma_f32_32x32x16_bf16 v[2:17], v[70:73], v[74:77], v[2:17]
	s_waitcnt lgkmcnt(0)
	v_mfma_f32_32x32x16_bf16 v[18:33], v[70:73], v[78:81], v[18:33]
	s_waitcnt vmcnt(6)
	s_barrier
; #define MFMA(a, b, c) __builtin_amdgcn_mfma_f32_32x32x16_bf16((a), (b), (c), 0, 0, 0)
; template <int AI, int BI>
; DI void gemm_stage(const u16* __restrict__ A, int lda, const u16* __restrict__ B, int ldb, char* buf, int tid) {
; #pragma unroll
;   for (int i = 0; i < 2 * AI; ++i) {
;     const int S = tid + NTHR * i, row = S >> 3, c = (S & 7) ^ ((row >> 1) & 7);
;     __builtin_amdgcn_global_load_lds((const unsigned*)(A + (size_t)row * lda + c * 8), (__attribute__((address_space(3))) unsigned*)(buf + S * 16), 16, 0, 0);
;   }
; #pragma unroll
;   for (int i = 0; i < 2 * BI; ++i) {
;     const int S = tid + NTHR * i, row = S >> 3, c = (S & 7) ^ ((row >> 1) & 7);
;     __builtin_amdgcn_global_load_lds((const unsigned*)(B + (size_t)row * ldb + c * 8), (__attribute__((address_space(3))) unsigned*)(buf + 16384 + S * 16), 16, 0, 0);
;   }
; }
; template <int AI, int BI>
; DI void gemm_tile(const u16* __restrict__ A, int lda, const u16* __restrict__ B, int ldb, int nk, bool swap,
;                   f32x16 (&acc)[AI][BI], char* lds) {
;     ...
;   for (int kt = 0; kt < nk; ++kt) {
;     const char* cur = lds + (kt & 1) * 32768;
;     if (kt + 1 < nk) gemm_stage<AI, BI>(A + (kt + 1) * 64, lda, B + (kt + 1) * 64, ldb, lds + ((kt + 1) & 1) * 32768, tid);
; #pragma unroll
;     for (int ks = 0; ks < 4; ++ks) {
;       const int co = ((ks * 2 + h) ^ sw) << 4;
;       s16x8 fa[AI], fb[BI];
; #pragma unroll
;       for (int i = 0; i < AI; ++i) fa[i] = *(const s16x8*)(cur + offA + i * 4096 + co);
; #pragma unroll
;       for (int i = 0; i < BI; ++i) fb[i] = *(const s16x8*)(cur + offB + i * 4096 + co);
; #pragma unroll
;       for (int i = 0; i < AI; ++i)
; #pragma unroll
;         for (int j = 0; j < BI; ++j) acc[i][j] = MFMA(fa[i], fb[j], acc[i][j]);
;     }
;     asm volatile("s_waitcnt vmcnt(0)" ::: "memory");
;     __syncthreads();
	s_add_u32 m0, s17, 49152
	s_nop 0
	global_load_lds_dwordx4 v90, s[8:9]
	s_add_u32 m0, s17, 53248
	s_nop 0
	global_load_lds_dwordx4 v91, s[8:9]
	s_add_u32 m0, s17, 0
	s_nop 0
	global_load_lds_dwordx4 v90, s[28:29]
	s_add_u32 m0, s17, 4096
	s_nop 0
	global_load_lds_dwordx4 v91, s[28:29]
	s_add_u32 m0, s17, 8192
	s_nop 0
	global_load_lds_dwordx4 v92, s[28:29]
	s_add_u32 m0, s17, 12288
	s_nop 0
	global_load_lds_dwordx4 v93, s[28:29]
	s_add_u32 s8, s8, 0x80
	s_addc_u32 s9, s9, 0
	s_add_u32 s28, s28, 0x80
	s_addc_u32 s29, s29, 0
	ds_read_b128 v[34:37], v82 offset:8192
	ds_read_b128 v[38:41], v86 offset:16384
	ds_read_b128 v[42:45], v86 offset:20480
	ds_read_b128 v[46:49], v83 offset:8192
	ds_read_b128 v[50:53], v87 offset:16384
	ds_read_b128 v[54:57], v87 offset:20480
	ds_read_b128 v[58:61], v84 offset:8192
	ds_read_b128 v[62:65], v88 offset:16384
	ds_read_b128 v[66:69], v88 offset:20480
	ds_read_b128 v[70:73], v85 offset:8192
	ds_read_b128 v[74:77], v89 offset:16384
	ds_read_b128 v[78:81], v89 offset:20480
	s_waitcnt lgkmcnt(10)
	v_mfma_f32_32x32x16_bf16 v[2:17], v[34:37], v[38:41], v[2:17]
	s_waitcnt lgkmcnt(9)
	v_mfma_f32_32x32x16_bf16 v[18:33], v[34:37], v[42:45], v[18:33]
	s_waitcnt lgkmcnt(7)
	v_mfma_f32_32x32x16_bf16 v[2:17], v[46:49], v[50:53], v[2:17]
	s_waitcnt lgkmcnt(6)
	v_mfma_f32_32x32x16_bf16 v[18:33], v[46:49], v[54:57], v[18:33]
	s_waitcnt lgkmcnt(4)
	v_mfma_f32_32x32x16_bf16 v[2:17], v[58:61], v[62:65], v[2:17]
	s_waitcnt lgkmcnt(3)
	v_mfma_f32_32x32x16_bf16 v[18:33], v[58:61], v[66:69], v[18:33]
	s_waitcnt lgkmcnt(1)
	v_mfma_f32_32x32x16_bf16 v[2:17], v[70:73], v[74:77], v[2:17]
	s_waitcnt lgkmcnt(0)
	v_mfma_f32_32x32x16_bf16 v[18:33], v[70:73], v[78:81], v[18:33]
	s_waitcnt vmcnt(6)
	s_barrier
	s_add_u32 m0, s17, 57344
	s_nop 0
	global_load_lds_dwordx4 v90, s[8:9]
	s_add_u32 m0, s17, 61440
	s_nop 0
	global_load_lds_dwordx4 v91, s[8:9]
	s_add_u32 m0, s17, 16384
	s_nop 0
	global_load_lds_dwordx4 v90, s[28:29]
	s_add_u32 m0, s17, 20480
	s_nop 0
	global_load_lds_dwordx4 v91, s[28:29]
	s_add_u32 m0, s17, 24576
	s_nop 0
	global_load_lds_dwordx4 v92, s[28:29]
	s_add_u32 m0, s17, 28672
	s_nop 0
	global_load_lds_dwordx4 v93, s[28:29]
	s_add_u32 s8, s8, 0x80
	s_addc_u32 s9, s9, 0
	s_add_u32 s28, s28, 0x80
	s_addc_u32 s29, s29, 0
	ds_read_b128 v[34:37], v82 offset:16512
	ds_read_b128 v[38:41], v86 offset:32768
	ds_read_b128 v[42:45], v86 offset:36864
	ds_read_b128 v[46:49], v83 offset:16512
	ds_read_b128 v[50:53], v87 offset:32768
	ds_read_b128 v[54:57], v87 offset:36864
	ds_read_b128 v[58:61], v84 offset:16512
	ds_read_b128 v[62:65], v88 offset:32768
	ds_read_b128 v[66:69], v88 offset:36864
	ds_read_b128 v[70:73], v85 offset:16512
	ds_read_b128 v[74:77], v89 offset:32768
	ds_read_b128 v[78:81], v89 offset:36864
	s_waitcnt lgkmcnt(10)
	v_mfma_f32_32x32x16_bf16 v[2:17], v[34:37], v[38:41], v[2:17]
	s_waitcnt lgkmcnt(9)
	v_mfma_f32_32x32x16_bf16 v[18:33], v[34:37], v[42:45], v[18:33]
	s_waitcnt lgkmcnt(7)
	v_mfma_f32_32x32x16_bf16 v[2:17], v[46:49], v[50:53], v[2:17]
	s_waitcnt lgkmcnt(6)
	v_mfma_f32_32x32x16_bf16 v[18:33], v[46:49], v[54:57], v[18:33]
	s_waitcnt lgkmcnt(4)
	v_mfma_f32_32x32x16_bf16 v[2:17], v[58:61], v[62:65], v[2:17]
	s_waitcnt lgkmcnt(3)
	v_mfma_f32_32x32x16_bf16 v[18:33], v[58:61], v[66:69], v[18:33]
	s_waitcnt lgkmcnt(1)
	v_mfma_f32_32x32x16_bf16 v[2:17], v[70:73], v[74:77], v[2:17]
	s_waitcnt lgkmcnt(0)
	v_mfma_f32_32x32x16_bf16 v[18:33], v[70:73], v[78:81], v[18:33]
	s_sub_u32 s18, s18, 1
	s_cmp_lg_u32 s18, 0
	s_cbranch_scc1 .Lgc1_kloop
	s_waitcnt vmcnt(6)
	s_barrier
	s_add_u32 m0, s17, 65664
	s_nop 0
	global_load_lds_dwordx4 v90, s[8:9]
	s_add_u32 m0, s17, 69760
	s_nop 0
	global_load_lds_dwordx4 v91, s[8:9]
	s_add_u32 m0, s17, 32768
	s_nop 0
	global_load_lds_dwordx4 v90, s[28:29]
	s_add_u32 m0, s17, 36864
	s_nop 0
	global_load_lds_dwordx4 v91, s[28:29]
	s_add_u32 m0, s17, 40960
	s_nop 0
	global_load_lds_dwordx4 v92, s[28:29]
	s_add_u32 m0, s17, 45056
	s_nop 0
	global_load_lds_dwordx4 v93, s[28:29]
	s_add_u32 s8, s8, 0x80
	s_addc_u32 s9, s9, 0
	s_add_u32 s28, s28, 0x80
	s_addc_u32 s29, s29, 0
	ds_read_b128 v[34:37], v82 offset:0
	ds_read_b128 v[38:41], v86 offset:0
	ds_read_b128 v[42:45], v86 offset:4096
	ds_read_b128 v[46:49], v83 offset:0
	ds_read_b128 v[50:53], v87 offset:0
	ds_read_b128 v[54:57], v87 offset:4096
	ds_read_b128 v[58:61], v84 offset:0
	ds_read_b128 v[62:65], v88 offset:0
	ds_read_b128 v[66:69], v88 offset:4096
	ds_read_b128 v[70:73], v85 offset:0
	ds_read_b128 v[74:77], v89 offset:0
	ds_read_b128 v[78:81], v89 offset:4096
	s_waitcnt lgkmcnt(10)
	v_mfma_f32_32x32x16_bf16 v[2:17], v[34:37], v[38:41], v[2:17]
	s_waitcnt lgkmcnt(9)
	v_mfma_f32_32x32x16_bf16 v[18:33], v[34:37], v[42:45], v[18:33]
	s_waitcnt lgkmcnt(7)
	v_mfma_f32_32x32x16_bf16 v[2:17], v[46:49], v[50:53], v[2:17]
	s_waitcnt lgkmcnt(6)
	v_mfma_f32_32x32x16_bf16 v[18:33], v[46:49], v[54:57], v[18:33]
	s_waitcnt lgkmcnt(4)
	v_mfma_f32_32x32x16_bf16 v[2:17], v[58:61], v[62:65], v[2:17]
	s_waitcnt lgkmcnt(3)
	v_mfma_f32_32x32x16_bf16 v[18:33], v[58:61], v[66:69], v[18:33]
	s_waitcnt lgkmcnt(1)
	v_mfma_f32_32x32x16_bf16 v[2:17], v[70:73], v[74:77], v[2:17]
	s_waitcnt lgkmcnt(0)
	v_mfma_f32_32x32x16_bf16 v[18:33], v[70:73], v[78:81], v[18:33]
	s_waitcnt vmcnt(6)
	s_barrier
; #define MFMA(a, b, c) __builtin_amdgcn_mfma_f32_32x32x16_bf16((a), (b), (c), 0, 0, 0)
; template <int AI, int BI>
; DI void gemm_tile(const u16* __restrict__ A, int lda, const u16* __restrict__ B, int ldb, int nk, bool swap,
;                   f32x16 (&acc)[AI][BI], char* lds) {
;     ...
;   for (int kt = 0; kt < nk; ++kt) {
;     const char* cur = lds + (kt & 1) * 32768;
;     if (kt + 1 < nk) gemm_stage<AI, BI>(A + (kt + 1) * 64, lda, B + (kt + 1) * 64, ldb, lds + ((kt + 1) & 1) * 32768, tid);
; #pragma unroll
;     for (int ks = 0; ks < 4; ++ks) {
;       const int co = ((ks * 2 + h) ^ sw) << 4;
;       s16x8 fa[AI], fb[BI];
; #pragma unroll
;       for (int i = 0; i < AI; ++i) fa[i] = *(const s16x8*)(cur + offA + i * 4096 + co);
; #pragma unroll
;       for (int i = 0; i < BI; ++i) fb[i] = *(const s16x8*)(cur + offB + i * 4096 + co);
; #pragma unroll
;       for (int i = 0; i < AI; ++i)
; #pragma unroll
;         for (int j = 0; j < BI; ++j) acc[i][j] = MFMA(fa[i], fb[j], acc[i][j]);
;     }
;     asm volatile("s_waitcnt vmcnt(0)" ::: "memory");
;     __syncthreads();
; DI bool next_tile(int rnd, int MT, int NT, int& mt, int& nt) {
;   const int G8 = gridDim.x >> 3, x = blockIdx.x & 7, slot = blockIdx.x >> 3;
;   const int T = (rnd * 8 + x) * G8 + slot;
;   if (T >= MT * NT) return false;
;   const int band = T / (NT * 8), rem = T - band * NT * 8;
;   nt = rem >> 3; mt = band * 8 + (rem & 7);
;   return true;
; }
	s_add_u32 m0, s17, 49152
	s_nop 0
	global_load_lds_dwordx4 v90, s[8:9]
	s_add_u32 m0, s17, 53248
	s_nop 0
	global_load_lds_dwordx4 v91, s[8:9]
	s_add_u32 m0, s17, 0
	s_nop 0
	global_load_lds_dwordx4 v90, s[28:29]
	s_add_u32 m0, s17, 4096
	s_nop 0
	global_load_lds_dwordx4 v91, s[28:29]
	s_add_u32 m0, s17, 8192
	s_nop 0
	global_load_lds_dwordx4 v92, s[28:29]
	s_add_u32 m0, s17, 12288
	s_nop 0
	global_load_lds_dwordx4 v93, s[28:29]
	s_add_u32 s8, s8, 0x80
	s_addc_u32 s9, s9, 0
	s_add_u32 s28, s28, 0x80
	s_addc_u32 s29, s29, 0
	ds_read_b128 v[34:37], v82 offset:8192
	ds_read_b128 v[38:41], v86 offset:16384
	ds_read_b128 v[42:45], v86 offset:20480
	ds_read_b128 v[46:49], v83 offset:8192
	ds_read_b128 v[50:53], v87 offset:16384
	ds_read_b128 v[54:57], v87 offset:20480
	ds_read_b128 v[58:61], v84 offset:8192
	ds_read_b128 v[62:65], v88 offset:16384
	ds_read_b128 v[66:69], v88 offset:20480
	ds_read_b128 v[70:73], v85 offset:8192
	ds_read_b128 v[74:77], v89 offset:16384
	ds_read_b128 v[78:81], v89 offset:20480
	s_waitcnt lgkmcnt(10)
	v_mfma_f32_32x32x16_bf16 v[2:17], v[34:37], v[38:41], v[2:17]
	s_waitcnt lgkmcnt(9)
	v_mfma_f32_32x32x16_bf16 v[18:33], v[34:37], v[42:45], v[18:33]
	s_waitcnt lgkmcnt(7)
	v_mfma_f32_32x32x16_bf16 v[2:17], v[46:49], v[50:53], v[2:17]
	s_waitcnt lgkmcnt(6)
	v_mfma_f32_32x32x16_bf16 v[18:33], v[46:49], v[54:57], v[18:33]
	s_waitcnt lgkmcnt(4)
	v_mfma_f32_32x32x16_bf16 v[2:17], v[58:61], v[62:65], v[2:17]
	s_waitcnt lgkmcnt(3)
	v_mfma_f32_32x32x16_bf16 v[18:33], v[58:61], v[66:69], v[18:33]
	s_waitcnt lgkmcnt(1)
	v_mfma_f32_32x32x16_bf16 v[2:17], v[70:73], v[74:77], v[2:17]
	s_waitcnt lgkmcnt(0)
	v_mfma_f32_32x32x16_bf16 v[18:33], v[70:73], v[78:81], v[18:33]
	s_waitcnt vmcnt(6)
	s_barrier
	ds_read_b128 v[34:37], v82 offset:16512
	ds_read_b128 v[38:41], v86 offset:32768
	ds_read_b128 v[42:45], v86 offset:36864
	ds_read_b128 v[46:49], v83 offset:16512
	ds_read_b128 v[50:53], v87 offset:32768
	ds_read_b128 v[54:57], v87 offset:36864
	ds_read_b128 v[58:61], v84 offset:16512
	ds_read_b128 v[62:65], v88 offset:32768
	ds_read_b128 v[66:69], v88 offset:36864
	ds_read_b128 v[70:73], v85 offset:16512
	ds_read_b128 v[74:77], v89 offset:32768
	ds_read_b128 v[78:81], v89 offset:36864
	s_waitcnt lgkmcnt(10)
	v_mfma_f32_32x32x16_bf16 v[2:17], v[34:37], v[38:41], v[2:17]
	s_waitcnt lgkmcnt(9)
	v_mfma_f32_32x32x16_bf16 v[18:33], v[34:37], v[42:45], v[18:33]
	s_waitcnt lgkmcnt(7)
	v_mfma_f32_32x32x16_bf16 v[2:17], v[46:49], v[50:53], v[2:17]
	s_waitcnt lgkmcnt(6)
	v_mfma_f32_32x32x16_bf16 v[18:33], v[46:49], v[54:57], v[18:33]
	s_waitcnt lgkmcnt(4)
	v_mfma_f32_32x32x16_bf16 v[2:17], v[58:61], v[62:65], v[2:17]
	s_waitcnt lgkmcnt(3)
	v_mfma_f32_32x32x16_bf16 v[18:33], v[58:61], v[66:69], v[18:33]
	s_waitcnt lgkmcnt(1)
	v_mfma_f32_32x32x16_bf16 v[2:17], v[70:73], v[74:77], v[2:17]
	s_waitcnt lgkmcnt(0)
	v_mfma_f32_32x32x16_bf16 v[18:33], v[70:73], v[78:81], v[18:33]
	s_waitcnt vmcnt(0)
	s_barrier
	ds_read_b128 v[34:37], v82 offset:0
	ds_read_b128 v[38:41], v86 offset:0
	ds_read_b128 v[42:45], v86 offset:4096
	ds_read_b128 v[46:49], v83 offset:0
	ds_read_b128 v[50:53], v87 offset:0
	ds_read_b128 v[54:57], v87 offset:4096
	ds_read_b128 v[58:61], v84 offset:0
	ds_read_b128 v[62:65], v88 offset:0
	ds_read_b128 v[66:69], v88 offset:4096
	ds_read_b128 v[70:73], v85 offset:0
	ds_read_b128 v[74:77], v89 offset:0
	ds_read_b128 v[78:81], v89 offset:4096
	s_waitcnt lgkmcnt(10)
	v_mfma_f32_32x32x16_bf16 v[2:17], v[34:37], v[38:41], v[2:17]
	s_waitcnt lgkmcnt(9)
	v_mfma_f32_32x32x16_bf16 v[18:33], v[34:37], v[42:45], v[18:33]
	s_waitcnt lgkmcnt(7)
	v_mfma_f32_32x32x16_bf16 v[2:17], v[46:49], v[50:53], v[2:17]
	s_waitcnt lgkmcnt(6)
	v_mfma_f32_32x32x16_bf16 v[18:33], v[46:49], v[54:57], v[18:33]
	s_waitcnt lgkmcnt(4)
	v_mfma_f32_32x32x16_bf16 v[2:17], v[58:61], v[62:65], v[2:17]
	s_waitcnt lgkmcnt(3)
	v_mfma_f32_32x32x16_bf16 v[18:33], v[58:61], v[66:69], v[18:33]
	s_waitcnt lgkmcnt(1)
	v_mfma_f32_32x32x16_bf16 v[2:17], v[70:73], v[74:77], v[2:17]
	s_waitcnt lgkmcnt(0)
	v_mfma_f32_32x32x16_bf16 v[18:33], v[70:73], v[78:81], v[18:33]
	s_add_u32 s36, s36, 0x200
	s_cmpk_lt_u32 s36, 0x580
	s_cbranch_scc0 .Lgc1_nopf
	s_barrier
	s_mul_i32 s37, s36, 0xba2f
	s_lshr_b32 s37, s37, 24
	s_mul_i32 s40, s37, 0x160
	s_sub_u32 s40, s36, s40
	s_lshr_b32 s41, s40, 3
	s_and_b32 s40, s40, 7
	s_lshl_b32 s37, s37, 3
	s_or_b32 s37, s37, s40
	s_lshl_b32 s37, s37, 6
	s_bitset1_b32 s37, 14
	s_lshl_b32 s46, s37, 11
	s_add_u32 s8, s10, s46
	s_addc_u32 s9, s11, 0
	s_lshl_b32 s46, s41, 18
	s_add_u32 s28, s12, s46
	s_addc_u32 s29, s13, 0
	s_add_u32 m0, s17, 49152
	s_nop 0
	global_load_lds_dwordx4 v90, s[8:9]
	s_add_u32 m0, s17, 53248
	s_nop 0
	global_load_lds_dwordx4 v91, s[8:9]
	s_add_u32 m0, s17, 0
	s_nop 0
	global_load_lds_dwordx4 v90, s[28:29]
	s_add_u32 m0, s17, 4096
	s_nop 0
	global_load_lds_dwordx4 v91, s[28:29]
	s_add_u32 m0, s17, 8192
	s_nop 0
	global_load_lds_dwordx4 v92, s[28:29]
	s_add_u32 m0, s17, 12288
	s_nop 0
	global_load_lds_dwordx4 v93, s[28:29]
	s_add_u32 s8, s8, 0x80
	s_addc_u32 s9, s9, 0
	s_add_u32 s28, s28, 0x80
	s_addc_u32 s29, s29, 0
	s_add_u32 m0, s17, 57344
	s_nop 0
	global_load_lds_dwordx4 v90, s[8:9]
	s_add_u32 m0, s17, 61440
	s_nop 0
	global_load_lds_dwordx4 v91, s[8:9]
	s_add_u32 m0, s17, 16384
	s_nop 0
	global_load_lds_dwordx4 v90, s[28:29]
	s_add_u32 m0, s17, 20480
	s_nop 0
	global_load_lds_dwordx4 v91, s[28:29]
	s_add_u32 m0, s17, 24576
	s_nop 0
	global_load_lds_dwordx4 v92, s[28:29]
	s_add_u32 m0, s17, 28672
	s_nop 0
	global_load_lds_dwordx4 v93, s[28:29]
	s_add_u32 s8, s8, 0x80
	s_addc_u32 s9, s9, 0
	s_add_u32 s28, s28, 0x80
	s_addc_u32 s29, s29, 0
; #define GAS __attribute__((address_space(1)))
; DI int opaque0() { int z = 0; asm volatile("" : "+v"(z)); return z; }
; template <int AI>
; DI void gu_tile(char* wsb, int sub, int m0, int n0, char* lds) {
;     ...
;   const int m0e = m0 + opaque0();
;   const int hc = (n0 >> 1) + wb * 32 + r;
;   GAS u16* HIDu = uptr(HID);
;   const unsigned ib = (unsigned)((m0e + wa * 32 * AI + 4 * h) * 2816 + hc);
; #pragma unroll
;   for (int ai = 0; ai < AI; ++ai)
; #pragma unroll
;     for (int reg = 0; reg < 16; ++reg) {
;       float g = acc[ai][0][reg], u = acc[ai][1][reg];
;       float v = g * __builtin_amdgcn_rcpf(1.f + __expf(-g)) * u;
;       HIDu[ib + (unsigned)((ai * 32 + (reg & 3) + 8 * (reg >> 2)) * 2816)] = f2bf(v);
;       if ((reg & 7) == 7) __builtin_amdgcn_sched_barrier(0);
;     }
; }
.Lgc1_nopf:
	s_nop 7
	s_nop 7
	v_mul_f32_e32 v66, 0xbfb8aa3b, v2
	v_mul_f32_e32 v68, 0xbfb8aa3b, v3
	v_exp_f32_e32 v66, v66
	v_exp_f32_e32 v68, v68
	v_add_u32_e32 v67, 0x0, v94
	v_add_f32_e32 v66, 1.0, v66
	v_add_f32_e32 v68, 1.0, v68
	v_rcp_f32_e32 v66, v66
	v_rcp_f32_e32 v68, v68
	v_add_u32_e32 v69, 0x1600, v94
	v_mul_f32_e32 v66, v2, v66
	v_mul_f32_e32 v68, v3, v68
	v_mul_f32_e32 v66, v18, v66
	v_mul_f32_e32 v68, v19, v68
	v_cvt_pk_bf16_f32 v66, v66, v66
	v_cvt_pk_bf16_f32 v68, v68, v68
	global_store_short v67, v66, s[34:35]
	global_store_short v69, v68, s[34:35]
	v_mul_f32_e32 v66, 0xbfb8aa3b, v4
	v_mul_f32_e32 v68, 0xbfb8aa3b, v5
	v_exp_f32_e32 v66, v66
	v_exp_f32_e32 v68, v68
	v_add_u32_e32 v67, 0x2c00, v94
	v_add_f32_e32 v66, 1.0, v66
	v_add_f32_e32 v68, 1.0, v68
	v_rcp_f32_e32 v66, v66
	v_rcp_f32_e32 v68, v68
	v_add_u32_e32 v69, 0x4200, v94
	v_mul_f32_e32 v66, v4, v66
	v_mul_f32_e32 v68, v5, v68
	v_mul_f32_e32 v66, v20, v66
	v_mul_f32_e32 v68, v21, v68
	v_cvt_pk_bf16_f32 v66, v66, v66
	v_cvt_pk_bf16_f32 v68, v68, v68
	global_store_short v67, v66, s[34:35]
	global_store_short v69, v68, s[34:35]
	v_mul_f32_e32 v66, 0xbfb8aa3b, v6
	v_mul_f32_e32 v68, 0xbfb8aa3b, v7
	v_exp_f32_e32 v66, v66
	v_exp_f32_e32 v68, v68
	v_add_u32_e32 v67, 0xb000, v94
	v_add_f32_e32 v66, 1.0, v66
	v_add_f32_e32 v68, 1.0, v68
	v_rcp_f32_e32 v66, v66
	v_rcp_f32_e32 v68, v68
	v_add_u32_e32 v69, 0xc600, v94
	v_mul_f32_e32 v66, v6, v66
	v_mul_f32_e32 v68, v7, v68
	v_mul_f32_e32 v66, v22, v66
	v_mul_f32_e32 v68, v23, v68
	v_cvt_pk_bf16_f32 v66, v66, v66
	v_cvt_pk_bf16_f32 v68, v68, v68
	global_store_short v67, v66, s[34:35]
	global_store_short v69, v68, s[34:35]
	v_mul_f32_e32 v66, 0xbfb8aa3b, v8
	v_mul_f32_e32 v68, 0xbfb8aa3b, v9
	v_exp_f32_e32 v66, v66
	v_exp_f32_e32 v68, v68
	v_add_u32_e32 v67, 0xdc00, v94
	v_add_f32_e32 v66, 1.0, v66
	v_add_f32_e32 v68, 1.0, v68
	v_rcp_f32_e32 v66, v66
	v_rcp_f32_e32 v68, v68
	v_add_u32_e32 v69, 0xf200, v94
	v_mul_f32_e32 v66, v8, v66
	v_mul_f32_e32 v68, v9, v68
	v_mul_f32_e32 v66, v24, v66
	v_mul_f32_e32 v68, v25, v68
	v_cvt_pk_bf16_f32 v66, v66, v66
	v_cvt_pk_bf16_f32 v68, v68, v68
	global_store_short v67, v66, s[34:35]
	global_store_short v69, v68, s[34:35]
	v_mul_f32_e32 v66, 0xbfb8aa3b, v10
	v_mul_f32_e32 v68, 0xbfb8aa3b, v11
	v_exp_f32_e32 v66, v66
	v_exp_f32_e32 v68, v68
	v_add_u32_e32 v67, 0x16000, v94
	v_add_f32_e32 v66, 1.0, v66
	v_add_f32_e32 v68, 1.0, v68
	v_rcp_f32_e32 v66, v66
	v_rcp_f32_e32 v68, v68
	v_add_u32_e32 v69, 0x17600, v94
	v_mul_f32_e32 v66, v10, v66
	v_mul_f32_e32 v68, v11, v68
	v_mul_f32_e32 v66, v26, v66
	v_mul_f32_e32 v68, v27, v68
	v_cvt_pk_bf16_f32 v66, v66, v66
	v_cvt_pk_bf16_f32 v68, v68, v68
	global_store_short v67, v66, s[34:35]
	global_store_short v69, v68, s[34:35]
	v_mul_f32_e32 v66, 0xbfb8aa3b, v12
	v_mul_f32_e32 v68, 0xbfb8aa3b, v13
	v_exp_f32_e32 v66, v66
	v_exp_f32_e32 v68, v68
	v_add_u32_e32 v67, 0x18c00, v94
	v_add_f32_e32 v66, 1.0, v66
	v_add_f32_e32 v68, 1.0, v68
	v_rcp_f32_e32 v66, v66
	v_rcp_f32_e32 v68, v68
	v_add_u32_e32 v69, 0x1a200, v94
	v_mul_f32_e32 v66, v12, v66
	v_mul_f32_e32 v68, v13, v68
	v_mul_f32_e32 v66, v28, v66
	v_mul_f32_e32 v68, v29, v68
	v_cvt_pk_bf16_f32 v66, v66, v66
	v_cvt_pk_bf16_f32 v68, v68, v68
	global_store_short v67, v66, s[34:35]
	global_store_short v69, v68, s[34:35]
	v_mul_f32_e32 v66, 0xbfb8aa3b, v14
	v_mul_f32_e32 v68, 0xbfb8aa3b, v15
	v_exp_f32_e32 v66, v66
	v_exp_f32_e32 v68, v68
	v_add_u32_e32 v67, 0x21000, v94
	v_add_f32_e32 v66, 1.0, v66
	v_add_f32_e32 v68, 1.0, v68
	v_rcp_f32_e32 v66, v66
	v_rcp_f32_e32 v68, v68
	v_add_u32_e32 v69, 0x22600, v94
	v_mul_f32_e32 v66, v14, v66
	v_mul_f32_e32 v68, v15, v68
	v_mul_f32_e32 v66, v30, v66
	v_mul_f32_e32 v68, v31, v68
	v_cvt_pk_bf16_f32 v66, v66, v66
	v_cvt_pk_bf16_f32 v68, v68, v68
	global_store_short v67, v66, s[34:35]
	global_store_short v69, v68, s[34:35]
	v_mul_f32_e32 v66, 0xbfb8aa3b, v16
	v_mul_f32_e32 v68, 0xbfb8aa3b, v17
	v_exp_f32_e32 v66, v66
	v_exp_f32_e32 v68, v68
	v_add_u32_e32 v67, 0x23c00, v94
	v_add_f32_e32 v66, 1.0, v66
	v_add_f32_e32 v68, 1.0, v68
	v_rcp_f32_e32 v66, v66
	v_rcp_f32_e32 v68, v68
	v_add_u32_e32 v69, 0x25200, v94
	v_mul_f32_e32 v66, v16, v66
	v_mul_f32_e32 v68, v17, v68
	v_mul_f32_e32 v66, v32, v66
	v_mul_f32_e32 v68, v33, v68
	v_cvt_pk_bf16_f32 v66, v66, v66
	v_cvt_pk_bf16_f32 v68, v68, v68
	global_store_short v67, v66, s[34:35]
	global_store_short v69, v68, s[34:35]
	s_mov_b32 s32, 1
	s_cmpk_lt_u32 s36, 0x580
	s_cbranch_scc1 .Lgc1_tile
	s_branch .Lgc1_exit

; #define TIDX opaque_tid()
; #define GAS __attribute__((address_space(1)))
; DI int opaque0() { int z = 0; asm volatile("" : "+v"(z)); return z; }
; template <int AI, int BI>
; DI void gemm_tile(const u16* __restrict__ A, int lda, const u16* __restrict__ B, int ldb, int nk, bool swap,
;                   f32x16 (&acc)[AI][BI], char* lds) {
;   const int tid = TIDX, lane = tid & 63, wid = tid >> 6;
;   gemm_stage<AI, BI>(A, lda, B, ldb, lds, tid);
;   asm volatile("s_waitcnt vmcnt(0)" ::: "memory");
;   __syncthreads();
;   const int wa = wid >> 1, wb = wid & 1, r = lane & 31, h = lane >> 5, sw = (r >> 1) & 7;
;   const int offA = (swap ? 16384 : 0) + (wa * 32 * AI + r) * 128;
; template <int AI>
; DI void gu_tile(char* wsb, int sub, int m0, int n0, char* lds) {
;   const u16* H = (const u16*)(wsb + OFF_H);
;   const u16* W = (const u16*)(wsb + OFF_W) + (sub ? W_GU1 : W_GU0);
;   u16* HID = (u16*)(wsb + OFF_HID);
;   const int lane = TIDX & 63, wid = TIDX >> 6, wa = wid >> 1, wb = wid & 1, r = lane & 31, h = lane >> 5;
;   f32x16 acc[AI][2]; zero_acc<AI, 2>(acc);
;   gemm_tile<AI, 2>(H + (size_t)m0 * 1024, 1024, W + (size_t)n0 * 1024, 1024, 16, false, acc, lds);
;   const int m0e = m0 + opaque0();
;   const int hc = (n0 >> 1) + wb * 32 + r;
;   GAS u16* HIDu = uptr(HID);
;   const unsigned ib = (unsigned)((m0e + wa * 32 * AI + 4 * h) * 2816 + hc);
.LBB0_1208:
	v_readlane_b32 s6, v244, 59
	v_readlane_b32 s10, v242, 9
	v_readlane_b32 s7, v244, 60
	v_readlane_b32 s11, v242, 10
	s_or_b64 s[6:7], s[10:11], s[6:7]
	s_and_b64 vcc, exec, s[6:7]
	s_cbranch_vccnz .LBB0_1212
	s_add_u32 s10, s8, 0x77b7000
	s_addc_u32 s11, s9, 0
	s_add_u32 s12, s8, 0x1d537000
	s_addc_u32 s13, s9, 0
	s_add_u32 s6, s8, 0x9bb7000
	s_addc_u32 s7, s9, 0
	v_readlane_b32 s14, v243, 18
	v_readlane_b32 s15, v243, 10
	v_readlane_b32 s16, v243, 8
	v_readlane_b32 s48, v243, 7
	v_readlane_b32 s49, v243, 9
	v_readlane_b32 s50, v243, 11
	s_movk_i32 s51, 0xb00
	s_mov_b32 s52, 0x1ffffe0
	s_mov_b32 s53, 0xffffe0
	s_mov_b64 s[56:57], 0x200
	s_mov_b64 s[64:65], 0x80
	s_mov_b64 s[66:67], 0x180
	s_mov_b64 s[68:69], 0x280
	s_mov_b64 s[70:71], 0x300
	s_mov_b64 s[72:73], 0x380
	s_mov_b64 s[74:75], 0x400
	s_mov_b64 s[76:77], 0x480
	s_mov_b64 s[80:81], 0x500
	s_mov_b64 s[82:83], 0x580
	s_mov_b64 s[84:85], 0x600
	s_waitcnt vmcnt(0)
	s_cmpk_lg_u32 s92, 0x200
	s_cbranch_scc1 .LBB0_1210
	v_and_b32_e32 v95, 31, v178
	v_bfe_u32 v96, v178, 5, 1
	v_bfe_u32 v97, v178, 1, 3
	v_bfe_u32 v98, v178, 7, 1
	v_lshl_add_u32 v98, v98, 5, v95
	v_lshlrev_b32_e32 v98, 7, v98
	v_add_u32_e32 v98, 0xc000, v98
	v_bfe_u32 v99, v178, 6, 1
	v_lshl_add_u32 v99, v99, 6, v95
	v_lshlrev_b32_e32 v99, 7, v99
	v_mov_b32_e32 v0, v96
	v_xor_b32_e32 v0, v0, v97
	v_lshlrev_b32_e32 v0, 4, v0
	v_add_u32_e32 v82, v98, v0
	v_add_u32_e32 v86, v99, v0
	v_add_u32_e32 v0, 2, v96
	v_xor_b32_e32 v0, v0, v97
	v_lshlrev_b32_e32 v0, 4, v0
	v_add_u32_e32 v83, v98, v0
	v_add_u32_e32 v87, v99, v0
	v_add_u32_e32 v0, 4, v96
	v_xor_b32_e32 v0, v0, v97
	v_lshlrev_b32_e32 v0, 4, v0
	v_add_u32_e32 v84, v98, v0
	v_add_u32_e32 v88, v99, v0
	v_add_u32_e32 v0, 6, v96
	v_xor_b32_e32 v0, v0, v97
	v_lshlrev_b32_e32 v0, 4, v0
	v_add_u32_e32 v85, v98, v0
	v_add_u32_e32 v89, v99, v0
	v_bfe_u32 v96, v178, 7, 1
	v_lshlrev_b32_e32 v96, 5, v96
	v_bfe_u32 v97, v178, 5, 1
	v_lshl_add_u32 v96, v97, 2, v96
	v_mul_u32_u24_e32 v96, 0xb00, v96
	v_bfe_u32 v97, v178, 6, 1
	v_lshl_add_u32 v97, v97, 5, v95
	v_add_u32_e32 v96, v96, v97
	v_lshlrev_b32_e32 v94, 1, v96
	v_lshrrev_b32_e32 v95, 3, v178
	v_and_b32_e32 v96, 7, v178
	v_bfe_u32 v97, v178, 4, 3
	v_xor_b32_e32 v96, v96, v97
	v_lshlrev_b32_e32 v96, 4, v96
	v_lshl_add_u32 v90, v95, 11, v96
	v_add_u32_e32 v91, 0x10000, v90
	v_add_u32_e32 v92, 0x20000, v90
	v_add_u32_e32 v93, 0x30000, v90
	v_lshrrev_b32_e32 v95, 6, v178
	s_nop 1
	v_readfirstlane_b32 s17, v95
	s_lshl_b32 s17, s17, 10
	s_mov_b32 s36, s14
	s_mul_i32 s37, s36, 0xba2f
	s_lshr_b32 s37, s37, 24
	s_mul_i32 s40, s37, 0x160
	s_sub_u32 s40, s36, s40
	s_lshr_b32 s41, s40, 3
	s_and_b32 s40, s40, 7
	s_lshl_b32 s37, s37, 3
	s_or_b32 s37, s37, s40
	s_lshl_b32 s37, s37, 6
	s_bitset1_b32 s37, 14
	s_lshl_b32 s46, s37, 11
	s_add_u32 s8, s10, s46
	s_addc_u32 s9, s11, 0
	s_lshl_b32 s46, s41, 18
	s_add_u32 s28, s12, s46
	s_addc_u32 s29, s13, 0
	s_barrier
	s_add_u32 m0, s17, 49152
	s_nop 0
	global_load_lds_dwordx4 v90, s[8:9]
	s_add_u32 m0, s17, 53248
	s_nop 0
	global_load_lds_dwordx4 v91, s[8:9]
	s_add_u32 m0, s17, 0
	s_nop 0
	global_load_lds_dwordx4 v90, s[28:29]
	s_add_u32 m0, s17, 4096
	s_nop 0
	global_load_lds_dwordx4 v91, s[28:29]
	s_add_u32 m0, s17, 8192
	s_nop 0
	global_load_lds_dwordx4 v92, s[28:29]
	s_add_u32 m0, s17, 12288
	s_nop 0
	global_load_lds_dwordx4 v93, s[28:29]
	s_add_u32 s8, s8, 0x80
	s_addc_u32 s9, s9, 0
	s_add_u32 s28, s28, 0x80
	s_addc_u32 s29, s29, 0
	s_add_u32 m0, s17, 57344
	s_nop 0
	global_load_lds_dwordx4 v90, s[8:9]
	s_add_u32 m0, s17, 61440
	s_nop 0
	global_load_lds_dwordx4 v91, s[8:9]
	s_add_u32 m0, s17, 16384
	s_nop 0
	global_load_lds_dwordx4 v90, s[28:29]
	s_add_u32 m0, s17, 20480
	s_nop 0
	global_load_lds_dwordx4 v91, s[28:29]
	s_add_u32 m0, s17, 24576
	s_nop 0
	global_load_lds_dwordx4 v92, s[28:29]
	s_add_u32 m0, s17, 28672
	s_nop 0
	global_load_lds_dwordx4 v93, s[28:29]
	s_add_u32 s8, s8, 0x80
	s_addc_u32 s9, s9, 0
	s_add_u32 s28, s28, 0x80
	s_addc_u32 s29, s29, 0
	s_mov_b32 s32, 0
